# split-phase seam 4 too: XCD-local dependency for the pool items, cross-XCD release awaited before the bvec/attention part
# speedup vs baseline: 1.0190x; 1.0075x over previous
.LBB0_782:
	s_mov_b32 s101, 0
	s_cmp_gt_i32 s69, 5
	s_cselect_b64 s[0:1], -1, 0
	s_and_b64 s[2:3], s[18:19], s[0:1]
	s_andn2_b64 vcc, exec, s[2:3]
	s_cbranch_vccnz .LBB0_836
	v_mov_b32_e32 v0, 0x20040
	ds_read_b32 v1, v0 offset:16
	ds_read_b32 v3, v0 offset:8
	s_waitcnt lgkmcnt(0)
	v_readfirstlane_b32 s6, v1
	s_nop 3
	s_cmp_eq_u32 s6, 0
	s_cbranch_scc1 .Ls4_orig
	s_waitcnt vmcnt(0)
	s_barrier
	v_cmp_gt_u32_e32 vcc, 64, v199
	s_cbranch_vccz .Ls4_done
	s_lshl_b32 s6, s33, 8
	s_add_u32 s6, s92, s6
	s_addc_u32 s7, s93, 0
	v_mov_b32_e32 v0, 0x1400
	v_mov_b32_e32 v1, 1
	s_lshl_b32 s10, s33, 7
	s_add_u32 s10, s10, 0x3a00
	v_lshl_add_u32 v4, v199, 2, s10
	v_lshl_add_u32 v3, v3, 2, s10
	v_cmp_eq_u32_e32 vcc, 0, v199
	s_and_saveexec_b64 s[12:13], vcc
	global_store_dword v3, v1, s[92:93]
	global_atomic_add v2, v0, v1, s[6:7] sc0
	s_mov_b64 exec, s[12:13]
	s_waitcnt vmcnt(0)
	v_readfirstlane_b32 s11, v2
	s_nop 3
	s_lshr_b32 s101, s11, 5
	s_add_i32 s101, s101, 1
	s_and_b32 s11, s11, 31
	s_cmp_eq_u32 s11, 31
	s_cbranch_scc0 .Ls4_wait
	buffer_wbl2 sc1
	s_waitcnt vmcnt(0)
	v_mov_b32_e32 v0, 0xfc03000
	s_and_saveexec_b64 s[12:13], vcc
	global_atomic_add v2, v0, v1, s[30:31] offset:1024 sc0
	s_mov_b64 exec, s[12:13]
	s_waitcnt vmcnt(0)
	v_readfirstlane_b32 s11, v2
	s_nop 3
	s_and_b32 s11, s11, 7
	s_cmp_eq_u32 s11, 7
	s_cbranch_scc0 .Ls4_wait
	v_mov_b32_e32 v0, 0xfc03500
	s_and_saveexec_b64 s[12:13], vcc
	global_atomic_add v0, v1, s[30:31]
	s_mov_b64 exec, s[12:13]

.Ls4_poll:
	global_load_dword v5, v4, s[92:93] sc1
	s_waitcnt vmcnt(0)
	v_cmp_gt_u32_e32 vcc, 1, v5
	s_cbranch_vccz .Ls4_got
	s_sleep 1
	s_sub_u32 s14, s14, 1
	s_cmp_lg_u32 s14, 0
	s_cbranch_scc1 .Ls4_poll

.Ls4_orig:
	s_waitcnt vmcnt(0)
	s_waitcnt vmcnt(0) lgkmcnt(0)
	s_barrier
	s_mov_b64 s[4:5], exec
	v_readlane_b32 s2, v255, 1
	v_readlane_b32 s3, v255, 2
	s_and_b64 s[2:3], s[4:5], s[2:3]
	s_mov_b64 exec, s[2:3]
	s_cbranch_execz .LBB0_835
	s_add_i32 s2, 0, 0x20040
	v_mov_b32_e32 v0, s2
	s_waitcnt vmcnt(0) expcnt(0) lgkmcnt(0)
	ds_read_b32 v2, v0
	s_add_i32 s2, 0, 0x20044
	v_mov_b32_e32 v0, s2
	ds_read_b32 v0, v0
	s_waitcnt lgkmcnt(1)
	v_cmp_ne_u32_e32 vcc, 0, v2
	s_cbranch_vccnz .LBB0_799
	s_add_u32 s6, s30, 0xfc00200
	s_addc_u32 s7, s31, 0
	s_add_u32 s8, s30, 0xfc00400
	s_addc_u32 s9, s31, 0
	s_add_u32 s12, s30, 0xfc00500
	s_addc_u32 s13, s31, 0
	s_add_u32 s18, s30, 0xfc00600
	s_addc_u32 s19, s31, 0
	s_add_u32 s20, s30, 0xfc00700
	s_addc_u32 s21, s31, 0
	s_add_u32 s24, s30, 0xfc00800
	s_addc_u32 s25, s31, 0
	s_add_u32 s26, s30, 0xfc00900
	s_addc_u32 s27, s31, 0
	s_add_u32 s42, s30, 0xfc00a00
	s_addc_u32 s43, s31, 0
	s_add_u32 s46, s30, 0xfc00b00
	s_addc_u32 s47, s31, 0
	s_add_u32 s48, s30, 0xfc00c00
	s_addc_u32 s49, s31, 0
	s_add_u32 s50, s30, 0xfc00d00
	s_addc_u32 s51, s31, 0
	s_add_u32 s52, s30, 0xfc00e00
	s_addc_u32 s53, s31, 0
	s_add_u32 s54, s30, 0xfc00f00
	s_addc_u32 s55, s31, 0
	s_add_u32 s56, s30, 0xfc01000
	s_addc_u32 s57, s31, 0
	s_add_u32 s58, s30, 0xfc01100
	s_addc_u32 s59, s31, 0
	s_add_u32 s60, s30, 0xfc01200
	v_readlane_b32 s2, v255, 0
	s_addc_u32 s61, s31, 0
	s_mul_i32 s2, s35, s2
	s_add_u32 s62, s30, 0xfc01300
	s_mul_i32 s2, s2, s34
	s_addc_u32 s63, s31, 0
	s_mov_b32 s3, 1
	v_mov_b32_e32 v16, 0
	s_branch .LBB0_787

.LBB0_1394:
	s_cmp_eq_u32 s98, 1
	s_cbranch_scc0 .Lg4_skip
	s_cmp_eq_u32 s101, 0
	s_cbranch_scc1 .Lg4_bar
	v_mov_b32_e32 v0, 0xfc03500
	s_mov_b32 s100, 0x8000
.Lg4_poll:
	global_load_dword v1, v0, s[30:31] sc1
	s_waitcnt vmcnt(0)
	v_cmp_le_u32_e32 vcc, s101, v1
	s_cbranch_vccnz .Lg4_got
	s_sleep 1
	s_sub_u32 s100, s100, 1
	s_cmp_lg_u32 s100, 0
	s_cbranch_scc1 .Lg4_poll
.Lg4_got:
	s_mov_b32 s101, 0
	buffer_inv sc1
	s_waitcnt vmcnt(0)
.Lg4_bar:
	s_barrier
.Lg4_skip:
	s_cmpk_gt_i32 s44, 0x15ff
	s_cbranch_scc1 .LBB0_1399
	v_lshlrev_b32_e32 v0, 6, v222
	v_mov_b32_e32 v1, 0
	v_lshl_add_u64 v[64:65], s[30:31], 0, v[0:1]
	v_add_co_u32_e32 v18, vcc, 0x2f06000, v64
	s_mov_b64 s[0:1], 0x2f06000
	s_nop 0
	v_addc_co_u32_e32 v19, vcc, 0, v65, vcc
	v_add_co_u32_e32 v34, vcc, 0x2f0f000, v64
	v_lshl_add_u64 v[16:17], v[64:65], 0, s[0:1]
	s_nop 0
	v_addc_co_u32_e32 v35, vcc, 0, v65, vcc
	s_mov_b64 s[0:1], 0x2f0f000
	v_add_co_u32_e32 v50, vcc, 0x2f18000, v64
	v_lshl_add_u64 v[32:33], v[64:65], 0, s[0:1]
	s_mov_b64 s[0:1], 0x2f18000
	v_addc_co_u32_e32 v51, vcc, 0, v65, vcc
	v_lshl_add_u64 v[48:49], v[64:65], 0, s[0:1]
	s_mov_b64 s[0:1], 0x2f21000
	v_add_co_u32_e32 v68, vcc, 0x2f21000, v64
	v_lshl_add_u64 v[66:67], v[64:65], 0, s[0:1]
	s_nop 0
	v_addc_co_u32_e32 v69, vcc, 0, v65, vcc
	s_mov_b64 s[0:1], 0x2f2a000
	v_lshl_add_u64 v[80:81], v[64:65], 0, s[0:1]
	v_add_co_u32_e32 v82, vcc, 0x2f2a000, v64
	global_load_dwordx4 v[0:3], v[16:17], off offset:16
	global_load_dwordx4 v[4:7], v[16:17], off offset:32
	global_load_dwordx4 v[8:11], v[18:19], off
	global_load_dwordx4 v[12:15], v[16:17], off offset:48
	s_nop 0
	global_load_dwordx4 v[16:19], v[32:33], off offset:16
	global_load_dwordx4 v[20:23], v[32:33], off offset:32
	global_load_dwordx4 v[24:27], v[34:35], off
	global_load_dwordx4 v[28:31], v[32:33], off offset:48
	s_nop 0
	global_load_dwordx4 v[32:35], v[48:49], off offset:16
	global_load_dwordx4 v[36:39], v[48:49], off offset:32
	global_load_dwordx4 v[40:43], v[50:51], off
	global_load_dwordx4 v[44:47], v[48:49], off offset:48
	s_nop 0
	global_load_dwordx4 v[48:51], v[66:67], off offset:16
	global_load_dwordx4 v[52:55], v[66:67], off offset:32
	global_load_dwordx4 v[56:59], v[68:69], off
	global_load_dwordx4 v[60:63], v[66:67], off offset:48
	v_addc_co_u32_e32 v83, vcc, 0, v65, vcc
	global_load_dwordx4 v[64:67], v[80:81], off offset:16
	global_load_dwordx4 v[68:71], v[80:81], off offset:32
	global_load_dwordx4 v[72:75], v[82:83], off
	global_load_dwordx4 v[76:79], v[80:81], off offset:48
	v_mbcnt_lo_u32_b32 v80, -1, 0
	v_mbcnt_hi_u32_b32 v80, -1, v80
	v_and_b32_e32 v81, 64, v80
	v_add_u32_e32 v81, 64, v81
	v_xor_b32_e32 v82, 1, v80
	v_cmp_lt_i32_e32 vcc, v82, v81
	v_xor_b32_e32 v83, 2, v80
	v_xor_b32_e32 v84, 4, v80
	v_cndmask_b32_e32 v82, v80, v82, vcc
	v_cmp_lt_i32_e32 vcc, v83, v81
	v_xor_b32_e32 v85, 8, v80
	v_xor_b32_e32 v86, 16, v80
	v_cndmask_b32_e32 v83, v80, v83, vcc
	v_cmp_lt_i32_e32 vcc, v84, v81
	v_xor_b32_e32 v87, 32, v80
	s_ashr_i32 s45, s44, 31
	v_cndmask_b32_e32 v84, v80, v84, vcc
	v_cmp_lt_i32_e32 vcc, v85, v81
	s_ashr_i32 s75, s74, 31
	s_lshl_b64 s[8:9], s[44:45], 11
	v_cndmask_b32_e32 v85, v80, v85, vcc
	v_cmp_lt_i32_e32 vcc, v86, v81
	v_cmp_eq_u32_e64 s[2:3], 0, v222
	v_lshlrev_b32_e32 v82, 2, v82
	v_cndmask_b32_e32 v86, v80, v86, vcc
	v_cmp_lt_i32_e32 vcc, v87, v81
	v_lshlrev_b32_e32 v83, 2, v83
	v_lshlrev_b32_e32 v84, 2, v84
	v_cndmask_b32_e32 v80, v80, v87, vcc
	v_lshlrev_b32_e32 v85, 2, v85
	v_lshlrev_b32_e32 v86, 2, v86
	v_lshlrev_b32_e32 v87, 2, v80
	s_lshl_b64 s[0:1], s[44:45], 2
	s_lshl_b64 s[6:7], s[74:75], 2
	v_lshl_or_b32 v80, v222, 5, s8
	v_mov_b32_e32 v81, s9
	s_lshl_b64 s[8:9], s[74:75], 11
	s_mov_b64 s[12:13], 0x1100000
	v_mov_b32_e32 v88, 0x2fa0000
	v_mov_b32_e32 v89, 0x2fa5000
	v_mov_b32_e32 v90, 0x2fab000
	v_mov_b32_e32 v91, 0x2fb0000
	v_mov_b32_e32 v92, 0x2fb6000
	s_branch .LBB0_1397
